# next-phase weight tiles touched (L2 warm-up loads) by waves 1-7 while waiting at the closing barrier before FFN-in and FFN-out phases
# baseline (speedup 1.0000x reference)
.LBB0_201:
	s_or_b64 exec, exec, s[0:1]
	s_cmp_eq_u32 s97, 0
	s_cbranch_scc1 .Lpf_skip_0
	v_readlane_b32 vcc_lo, v254, 6
	v_mbcnt_lo_u32_b32 v246, -1, 0
	v_mbcnt_hi_u32_b32 v246, -1, v246
	s_nop 1
	s_mul_hi_u32 s101, vcc_lo, 0x3280000
	s_mul_i32 s100, vcc_lo, 0x3280000
	s_add_u32 s100, s100, s46
	s_addc_u32 s101, s101, s47
	v_readlane_b32 vcc_lo, v253, 32
	v_readlane_b32 vcc_hi, v253, 33
	s_nop 1
	s_add_u32 s100, s100, vcc_lo
	s_addc_u32 s101, s101, vcc_hi
	v_readlane_b32 vcc_lo, v254, 53
	v_readlane_b32 vcc_hi, v254, 54
	s_nop 1
	s_and_b64 vcc, vcc, exec
	s_mov_b32 vcc_lo, 0x1000000
	s_cselect_b32 vcc_lo, vcc_lo, 0x2800000
	s_add_u32 s100, s100, vcc_lo
	s_addc_u32 s101, s101, 0
	v_add_u32_e32 v246, s97, v246
	v_subrev_u32_e32 v246, 64, v246
	v_and_b32_e32 v247, 0xff, v246
	v_lshrrev_b32_e32 v246, 8, v246
	v_lshlrev_b32_e32 v246, 7, v246
	v_lshl_add_u32 v246, v247, 13, v246
	global_load_dword v248, v246, s[100:101]
	global_load_dword v249, v246, s[100:101] offset:128
.Lpf_skip_0:
	s_mov_b64 s[0:1], 0
	s_barrier

.LBB0_872:
	s_or_b64 exec, exec, s[0:1]
	s_cmp_eq_u32 s97, 0
	s_cbranch_scc1 .Lpf_skip_1
	v_readlane_b32 vcc_lo, v254, 6
	v_mbcnt_lo_u32_b32 v246, -1, 0
	v_mbcnt_hi_u32_b32 v246, -1, v246
	s_nop 1
	s_mul_hi_u32 s101, vcc_lo, 0x3280000
	s_mul_i32 s100, vcc_lo, 0x3280000
	s_add_u32 s100, s100, s46
	s_addc_u32 s101, s101, s47
	v_readlane_b32 vcc_lo, v253, 3
	v_readlane_b32 vcc_hi, v253, 4
	s_nop 1
	s_add_u32 s100, s100, vcc_lo
	s_addc_u32 s101, s101, vcc_hi
	s_add_u32 s100, s100, 0x1800000
	s_addc_u32 s101, s101, 0
	v_add_u32_e32 v246, s97, v246
	v_subrev_u32_e32 v246, 64, v246
	v_and_b32_e32 v247, 0xff, v246
	v_lshrrev_b32_e32 v246, 8, v246
	v_lshlrev_b32_e32 v246, 7, v246
	v_lshl_add_u32 v246, v247, 11, v246
	global_load_dword v248, v246, s[100:101]
	global_load_dword v249, v246, s[100:101] offset:128

.LBB0_990:
	s_or_b64 exec, exec, s[0:1]
	s_cmp_eq_u32 s97, 0
	s_cbranch_scc1 .Lpf_skip_2
	v_readlane_b32 vcc_lo, v254, 6
	v_mbcnt_lo_u32_b32 v246, -1, 0
	v_mbcnt_hi_u32_b32 v246, -1, v246
	s_nop 1
	s_add_i32 vcc_lo, vcc_lo, 1
	s_mul_hi_u32 s101, vcc_lo, 0x3280000
	s_mul_i32 s100, vcc_lo, 0x3280000
	s_add_u32 s100, s100, s46
	s_addc_u32 s101, s101, s47
	v_readlane_b32 vcc_lo, v253, 3
	v_readlane_b32 vcc_hi, v253, 4
	s_nop 1
	s_add_u32 s100, s100, vcc_lo
	s_addc_u32 s101, s101, vcc_hi
	v_add_u32_e32 v246, s97, v246
	v_subrev_u32_e32 v246, 64, v246
	v_and_b32_e32 v247, 0xff, v246
	v_lshrrev_b32_e32 v246, 8, v246
	v_lshlrev_b32_e32 v246, 7, v246
	v_lshl_add_u32 v246, v247, 11, v246
	global_load_dword v248, v246, s[100:101]
	global_load_dword v249, v246, s[100:101] offset:128
